# idx job: level-1 histogram cleared inside scan A (one barrier and the clearing loop removed); job-start clearing with 16-byte stores
# speedup vs baseline: 1.0080x; 1.0080x over previous
; DI void idx_job(const Params& p, int b, int qg, unsigned char* smem) {
;     ...
;   const int t0 = qg * 16, ntile = qg + 1, tq = t0 + lm;
;   const bool selall = tq + 1 <= 256;
;   bf16x8 qf[8];
;   float wq[8];
;   {
;     const u16* qr = p.qix + (size_t)(b * TP + tq) * 256 + lg * 8;
;     const float* wr = p.wix + (size_t)(b * TP + tq) * 8;
; #pragma unroll
;     for (int j = 0; j < 8; ++j) { qf[j] = *(const bf16x8*)(qr + j * 32); wq[j] = wr[j]; }
;   }
;   for (int i = tid; i < 8192 + 2112; i += 256) hist[i] = 0u;
;   if (tid < 80) ccnt[tid] = 0u;
;   __syncthreads();
;   const u16* kbase = p.kix + (size_t)b * TP * 32;
;   const f32x4 z4 = {0.f, 0.f, 0.f, 0.f};
;   const u16* kp = kbase + (size_t)lm * 32 + lg * 8;
.Lidxsc_lo:
	s_mul_i32 s88, s88, 0x42000
	s_add_u32 s90, s90, s88
	s_addc_u32 s91, s91, 0
	s_sub_u32 s92, s90, 0x2000
	s_subb_u32 s93, s91, 0
	s_sub_u32 s94, s90, 0x1000
	s_subb_u32 s95, s91, 0
	v_lshl_add_u64 v[248:249], s[90:91], 0, v[250:251]
	v_lshl_add_u64 v[2:3], s[70:71], 0, v[2:3]
	v_and_b32_e32 v4, 48, v86
	v_mov_b32_e32 v5, v1
	v_lshl_add_u64 v[10:11], v[2:3], 0, v[4:5]
	v_lshlrev_b64 v[2:3], 5, v[0:1]
	v_lshl_add_u64 v[6:7], s[74:75], 0, v[2:3]
	global_load_dwordx4 v[38:41], v[10:11], off
	global_load_dwordx4 v[34:37], v[10:11], off offset:64
	global_load_dwordx4 v[2:5], v[6:7], off offset:16
	s_nop 0
	global_load_dwordx4 v[6:9], v[6:7], off
	s_nop 0
	global_load_dwordx4 v[30:33], v[10:11], off offset:128
	global_load_dwordx4 v[26:29], v[10:11], off offset:192
	global_load_dwordx4 v[22:25], v[10:11], off offset:256
	global_load_dwordx4 v[18:21], v[10:11], off offset:320
	global_load_dwordx4 v[14:17], v[10:11], off offset:384
	s_nop 0
	global_load_dwordx4 v[10:13], v[10:11], off offset:448
	v_add_u32_e32 v136, 0xffffff00, v86
	v_lshl_add_u32 v137, v86, 2, v96
	v_mov_b32_e32 v158, 0
	v_mov_b32_e32 v159, 0
	v_mov_b32_e32 v160, 0
	v_mov_b32_e32 v161, 0
	v_lshl_add_u32 v43, v86, 4, v96
	ds_write_b128 v43, v[158:161]
	ds_write_b128 v43, v[158:161] offset:4096
	ds_write_b128 v43, v[158:161] offset:8192
	ds_write_b128 v43, v[158:161] offset:12288
	ds_write_b128 v43, v[158:161] offset:16384
	ds_write_b128 v43, v[158:161] offset:20480
	ds_write_b128 v43, v[158:161] offset:24576
	ds_write_b128 v43, v[158:161] offset:28672
	ds_write_b128 v43, v[158:161] offset:32768
	ds_write_b128 v43, v[158:161] offset:36864
	v_cmp_gt_u32_e64 s[4:5], 16, v86
	s_and_saveexec_b64 s[2:3], s[4:5]
	ds_write_b128 v43, v[158:161] offset:40960
	s_or_b64 exec, exec, s[2:3]
	v_bfe_u32 v54, v86, 4, 2
	s_movk_i32 s2, 0x50
	v_and_b32_e32 v141, 63, v86
	v_mul_u32_u24_e32 v89, 0x1080, v42
	v_lshlrev_b32_e32 v43, 3, v54
	v_cmp_gt_i32_e32 vcc, s2, v86
	s_and_saveexec_b64 s[2:3], vcc
	v_lshl_add_u32 v0, v86, 2, v96
	ds_write_b32 v0, v1 offset:49408
	s_or_b64 exec, exec, s[2:3]
	s_waitcnt lgkmcnt(0)
	s_barrier
	s_load_dwordx16 s[60:75], s[0:1], 0x108
	v_mul_u32_u24_e32 v0, 0x21000, v42
	v_ashrrev_i32_e32 v109, 6, v86
	v_lshlrev_b32_e32 v0, 1, v0
	v_cmp_le_i32_e32 vcc, v109, v97
	s_waitcnt lgkmcnt(0)
	v_lshl_add_u64 v[44:45], s[72:73], 0, v[0:1]
	v_lshlrev_b32_e32 v0, 6, v88
	v_lshl_add_u64 v[44:45], v[44:45], 0, v[0:1]
	v_lshlrev_b32_e32 v0, 1, v43
	v_cndmask_b32_e32 v42, 0, v109, vcc
	v_lshl_add_u64 v[90:91], v[44:45], 0, v[0:1]
	v_ashrrev_i32_e32 v43, 31, v42
	v_add_u32_e32 v0, 4, v109
	v_lshlrev_b64 v[42:43], 10, v[42:43]
	v_cmp_le_i32_e32 vcc, v0, v97
	v_lshl_add_u64 v[92:93], v[90:91], 0, v[42:43]
	v_mov_b32_e32 v110, v0
	v_cndmask_b32_e32 v42, 0, v0, vcc
	v_ashrrev_i32_e32 v43, 31, v42
	v_lshlrev_b64 v[42:43], 10, v[42:43]
	v_lshl_add_u64 v[94:95], v[90:91], 0, v[42:43]
	global_load_dwordx4 v[42:45], v[92:93], off
	global_load_dwordx4 v[50:53], v[94:95], off
	v_cmp_lt_i32_e32 vcc, v0, v97
	v_mov_b32_e32 v111, v109
	s_and_saveexec_b64 s[2:3], vcc
	s_cbranch_execz .LBB0_398
	v_mov_b32_e32 v55, v88
	s_waitcnt vmcnt(8)
	v_mov_b32_e32 v56, v8
	v_mov_b32_e32 v57, v8
	v_mov_b32_e32 v58, v9
	v_mov_b32_e32 v59, v9
	v_mov_b32_e32 v60, v2
	v_mov_b32_e32 v61, v2
	v_mov_b32_e32 v62, v3
	v_mov_b32_e32 v63, v3
	v_mov_b32_e32 v64, v4
	v_mov_b32_e32 v65, v4
	v_mov_b32_e32 v66, v5
	v_mov_b32_e32 v67, v5
	s_mov_b64 s[6:7], 0
	v_mov_b32_e32 v111, v109
	s_waitcnt vmcnt(0)

; DI void idx_scan(const u32* hq, int need, u32* outbin, u32* outneed, int q, int lane) {
;   u32 c = 0;
; #pragma unroll
;   for (int w = 0; w < 8; ++w) { u32 v = hq[8 * lane + w]; c += (v & 0xffffu) + (v >> 16); }
;   u32 incl = c;
; #pragma unroll
;   for (int o = 1; o < 64; o <<= 1) { u32 v = __shfl_down(incl, o); if (lane + o < 64) incl += v; }
;   const u32 above = incl - c;
;   if ((int)above < need && need <= (int)incl) {
; DI void idx_job(const Params& p, int b, int qg, unsigned char* smem) {
;     ...
;   for (int qq = 0; qq < 4; ++qq) idx_scan(hist + (wave * 4 + qq) * 512, 256, binA, needB, wave * 4 + qq, lane);
;   __syncthreads();
;   for (int i = tid; i < 8192; i += 256) hist[i] = 0u;
.Lidx1_ne:
	v_lshl_add_u32 v46, v109, 13, v96
	v_and_b32_e32 v48, 63, v207
	v_lshl_add_u32 v47, v109, 4, v96
	v_lshl_add_u32 v46, v48, 5, v46
	v_add_u32_e32 v47, 0xc000, v47
	ds_read_b128 v[168:171], v46
	ds_read_b128 v[172:175], v46 offset:16
	ds_read_b128 v[176:179], v46 offset:2048
	ds_read_b128 v[180:183], v46 offset:2064
	ds_read_b128 v[184:187], v46 offset:4096
	ds_read_b128 v[188:191], v46 offset:4112
	ds_read_b128 v[226:229], v46 offset:6144
	ds_read_b128 v[230:233], v46 offset:6160
	v_mov_b32_e32 v238, 0x100
	v_mov_b32_e32 v239, 0x100
	v_mov_b32_e32 v240, 0x100
	v_mov_b32_e32 v241, 0x100
	s_waitcnt lgkmcnt(0)
	v_mov_b32_e32 v158, 0
	v_mov_b32_e32 v159, 0
	v_mov_b32_e32 v160, 0
	v_mov_b32_e32 v161, 0
	ds_write_b128 v46, v[158:161]
	ds_write_b128 v46, v[158:161] offset:16
	ds_write_b128 v46, v[158:161] offset:2048
	ds_write_b128 v46, v[158:161] offset:2064
	ds_write_b128 v46, v[158:161] offset:4096
	ds_write_b128 v46, v[158:161] offset:4112
	ds_write_b128 v46, v[158:161] offset:6144
	ds_write_b128 v46, v[158:161] offset:6160
	v_add3_u32 v192, v168, v169, v170
	v_add3_u32 v193, v176, v177, v178
	v_add3_u32 v194, v184, v185, v186
	v_add3_u32 v195, v226, v227, v228
	v_add3_u32 v192, v192, v171, v172
	v_add3_u32 v193, v193, v179, v180
	v_add3_u32 v194, v194, v187, v188
	v_add3_u32 v195, v195, v229, v230
	v_add3_u32 v192, v192, v173, v174
	v_add3_u32 v193, v193, v181, v182
	v_add3_u32 v194, v194, v189, v190
	v_add3_u32 v195, v195, v231, v232
	v_add_u32_e32 v192, v192, v175
	v_add_u32_e32 v193, v193, v183
	v_add_u32_e32 v194, v194, v191
	v_add_u32_e32 v195, v195, v233
	v_add_u32_sdwa v192, v192, v192 dst_sel:DWORD dst_unused:UNUSED_PAD src0_sel:WORD_0 src1_sel:WORD_1
	v_add_u32_sdwa v193, v193, v193 dst_sel:DWORD dst_unused:UNUSED_PAD src0_sel:WORD_0 src1_sel:WORD_1
	v_add_u32_sdwa v194, v194, v194 dst_sel:DWORD dst_unused:UNUSED_PAD src0_sel:WORD_0 src1_sel:WORD_1
	v_add_u32_sdwa v195, v195, v195 dst_sel:DWORD dst_unused:UNUSED_PAD src0_sel:WORD_0 src1_sel:WORD_1
	v_mov_b32_e32 v234, v192
	v_mov_b32_e32 v235, v193
	v_mov_b32_e32 v236, v194
	v_mov_b32_e32 v237, v195
	v_add_u32_dpp v234, v234, v234 row_shl:1 row_mask:0xf bank_mask:0xf
	v_add_u32_dpp v235, v235, v235 row_shl:1 row_mask:0xf bank_mask:0xf
	v_add_u32_dpp v236, v236, v236 row_shl:1 row_mask:0xf bank_mask:0xf
	v_add_u32_dpp v237, v237, v237 row_shl:1 row_mask:0xf bank_mask:0xf
	v_add_u32_dpp v234, v234, v234 row_shl:2 row_mask:0xf bank_mask:0xf
	v_add_u32_dpp v235, v235, v235 row_shl:2 row_mask:0xf bank_mask:0xf
	v_add_u32_dpp v236, v236, v236 row_shl:2 row_mask:0xf bank_mask:0xf
	v_add_u32_dpp v237, v237, v237 row_shl:2 row_mask:0xf bank_mask:0xf
	v_add_u32_dpp v234, v234, v234 row_shl:4 row_mask:0xf bank_mask:0xf
	v_add_u32_dpp v235, v235, v235 row_shl:4 row_mask:0xf bank_mask:0xf
	v_add_u32_dpp v236, v236, v236 row_shl:4 row_mask:0xf bank_mask:0xf
	v_add_u32_dpp v237, v237, v237 row_shl:4 row_mask:0xf bank_mask:0xf
	v_add_u32_dpp v234, v234, v234 row_shl:8 row_mask:0xf bank_mask:0xf
	v_add_u32_dpp v235, v235, v235 row_shl:8 row_mask:0xf bank_mask:0xf
	v_add_u32_dpp v236, v236, v236 row_shl:8 row_mask:0xf bank_mask:0xf
	v_add_u32_dpp v237, v237, v237 row_shl:8 row_mask:0xf bank_mask:0xf
	s_nop 1
	v_readlane_b32 s40, v234, 16
	v_readlane_b32 s41, v234, 32
	v_readlane_b32 s42, v234, 48
	v_readlane_b32 s43, v235, 16
	v_readlane_b32 s44, v235, 32
	v_readlane_b32 s45, v235, 48
	v_readlane_b32 s46, v236, 16
	v_readlane_b32 s47, v236, 32
	v_readlane_b32 s48, v236, 48
	v_readlane_b32 s49, v237, 16
	v_readlane_b32 s50, v237, 32
	v_readlane_b32 s51, v237, 48
	s_nop 0
	s_add_i32 s41, s41, s42
	s_add_i32 s40, s40, s41
	s_add_i32 s44, s44, s45
	s_add_i32 s43, s43, s44
	s_add_i32 s47, s47, s48
	s_add_i32 s46, s46, s47
	s_add_i32 s50, s50, s51
	s_add_i32 s49, s49, s50
	s_mov_b32 exec_lo, 0xffff
	s_mov_b32 exec_hi, 0
	v_add_u32_e32 v234, s40, v234
	v_add_u32_e32 v235, s43, v235
	v_add_u32_e32 v236, s46, v236
	v_add_u32_e32 v237, s49, v237
	s_mov_b32 exec_lo, 0xffff0000
	v_add_u32_e32 v234, s41, v234
	v_add_u32_e32 v235, s44, v235
	v_add_u32_e32 v236, s47, v236
	v_add_u32_e32 v237, s50, v237
	s_mov_b32 exec_lo, 0
	s_mov_b32 exec_hi, 0xffff
	v_add_u32_e32 v234, s42, v234
	v_add_u32_e32 v235, s45, v235
	v_add_u32_e32 v236, s48, v236
	v_add_u32_e32 v237, s51, v237
	s_mov_b64 exec, -1
	v_sub_u32_e32 v158, v234, v192
	v_sub_u32_e32 v159, v235, v193
	v_sub_u32_e32 v160, v236, v194
	v_sub_u32_e32 v161, v237, v195
	v_cmp_lt_u32_e64 s[4:5], v158, v238
	v_cmp_lt_u32_e64 s[6:7], v159, v239
	v_cmp_lt_u32_e64 s[8:9], v160, v240
	v_cmp_lt_u32_e64 s[28:29], v161, v241
	v_cmp_le_u32_e64 s[40:41], v238, v234
	v_cmp_le_u32_e64 s[42:43], v239, v235
	v_cmp_le_u32_e64 s[44:45], v240, v236
	v_cmp_le_u32_e64 s[46:47], v241, v237
	v_mov_b32_e32 v42, v158
	v_mov_b32_e32 v43, v159
	v_mov_b32_e32 v44, v160
	v_mov_b32_e32 v45, v161
	v_mov_b32_e32 v162, 15
	v_mov_b32_e32 v163, 15
	v_mov_b32_e32 v164, 15
	v_mov_b32_e32 v165, 15
	s_and_b64 s[40:41], s[40:41], s[4:5]
	s_and_b64 s[42:43], s[42:43], s[6:7]
	s_and_b64 s[44:45], s[44:45], s[8:9]
	s_and_b64 s[46:47], s[46:47], s[28:29]
	v_add_u32_sdwa v158, v175, v158 dst_sel:DWORD dst_unused:UNUSED_PAD src0_sel:WORD_1 src1_sel:DWORD
	v_add_u32_sdwa v159, v183, v159 dst_sel:DWORD dst_unused:UNUSED_PAD src0_sel:WORD_1 src1_sel:DWORD
	v_add_u32_sdwa v160, v191, v160 dst_sel:DWORD dst_unused:UNUSED_PAD src0_sel:WORD_1 src1_sel:DWORD
	v_add_u32_sdwa v161, v233, v161 dst_sel:DWORD dst_unused:UNUSED_PAD src0_sel:WORD_1 src1_sel:DWORD
	v_cmp_lt_u32_e64 s[4:5], v158, v238
	v_cmp_lt_u32_e64 s[6:7], v159, v239
	v_cmp_lt_u32_e64 s[8:9], v160, v240
	v_cmp_lt_u32_e64 s[28:29], v161, v241
; DI void idx_scan(const u32* hq, int need, u32* outbin, u32* outneed, int q, int lane) {
;     ...
;   if ((int)above < need && need <= (int)incl) {
;     u32 cum = above;
;     ...
;       u32 cnt = (hq[bin >> 1] >> ((bin & 1) * 16)) & 0xffffu;
;       if ((int)(cum + cnt) >= need) { outbin[q] = (u32)bin; outneed[q] = (u32)need - cum; break; }
;       cum += cnt;
;     }
	v_cndmask_b32_e64 v42, v42, v158, s[4:5]
	v_cndmask_b32_e64 v162, v162, 14, s[4:5]
	v_cndmask_b32_e64 v43, v43, v159, s[6:7]
	v_cndmask_b32_e64 v163, v163, 14, s[6:7]
	v_cndmask_b32_e64 v44, v44, v160, s[8:9]
	v_cndmask_b32_e64 v164, v164, 14, s[8:9]
	v_cndmask_b32_e64 v45, v45, v161, s[28:29]
	v_cndmask_b32_e64 v165, v165, 14, s[28:29]
	v_add_u32_sdwa v158, v175, v158 dst_sel:DWORD dst_unused:UNUSED_PAD src0_sel:WORD_0 src1_sel:DWORD
	v_add_u32_sdwa v159, v183, v159 dst_sel:DWORD dst_unused:UNUSED_PAD src0_sel:WORD_0 src1_sel:DWORD
	v_add_u32_sdwa v160, v191, v160 dst_sel:DWORD dst_unused:UNUSED_PAD src0_sel:WORD_0 src1_sel:DWORD
	v_add_u32_sdwa v161, v233, v161 dst_sel:DWORD dst_unused:UNUSED_PAD src0_sel:WORD_0 src1_sel:DWORD
	v_cmp_lt_u32_e64 s[4:5], v158, v238
	v_cmp_lt_u32_e64 s[6:7], v159, v239
	v_cmp_lt_u32_e64 s[8:9], v160, v240
	v_cmp_lt_u32_e64 s[28:29], v161, v241
	v_cndmask_b32_e64 v42, v42, v158, s[4:5]
	v_cndmask_b32_e64 v162, v162, 13, s[4:5]
	v_cndmask_b32_e64 v43, v43, v159, s[6:7]
	v_cndmask_b32_e64 v163, v163, 13, s[6:7]
	v_cndmask_b32_e64 v44, v44, v160, s[8:9]
	v_cndmask_b32_e64 v164, v164, 13, s[8:9]
	v_cndmask_b32_e64 v45, v45, v161, s[28:29]
	v_cndmask_b32_e64 v165, v165, 13, s[28:29]
	v_add_u32_sdwa v158, v174, v158 dst_sel:DWORD dst_unused:UNUSED_PAD src0_sel:WORD_1 src1_sel:DWORD
	v_add_u32_sdwa v159, v182, v159 dst_sel:DWORD dst_unused:UNUSED_PAD src0_sel:WORD_1 src1_sel:DWORD
	v_add_u32_sdwa v160, v190, v160 dst_sel:DWORD dst_unused:UNUSED_PAD src0_sel:WORD_1 src1_sel:DWORD
	v_add_u32_sdwa v161, v232, v161 dst_sel:DWORD dst_unused:UNUSED_PAD src0_sel:WORD_1 src1_sel:DWORD
	v_cmp_lt_u32_e64 s[4:5], v158, v238
	v_cmp_lt_u32_e64 s[6:7], v159, v239
	v_cmp_lt_u32_e64 s[8:9], v160, v240
	v_cmp_lt_u32_e64 s[28:29], v161, v241
	v_cndmask_b32_e64 v42, v42, v158, s[4:5]
	v_cndmask_b32_e64 v162, v162, 12, s[4:5]
	v_cndmask_b32_e64 v43, v43, v159, s[6:7]
	v_cndmask_b32_e64 v163, v163, 12, s[6:7]
	v_cndmask_b32_e64 v44, v44, v160, s[8:9]
	v_cndmask_b32_e64 v164, v164, 12, s[8:9]
	v_cndmask_b32_e64 v45, v45, v161, s[28:29]
	v_cndmask_b32_e64 v165, v165, 12, s[28:29]
	v_add_u32_sdwa v158, v174, v158 dst_sel:DWORD dst_unused:UNUSED_PAD src0_sel:WORD_0 src1_sel:DWORD
	v_add_u32_sdwa v159, v182, v159 dst_sel:DWORD dst_unused:UNUSED_PAD src0_sel:WORD_0 src1_sel:DWORD
	v_add_u32_sdwa v160, v190, v160 dst_sel:DWORD dst_unused:UNUSED_PAD src0_sel:WORD_0 src1_sel:DWORD
	v_add_u32_sdwa v161, v232, v161 dst_sel:DWORD dst_unused:UNUSED_PAD src0_sel:WORD_0 src1_sel:DWORD
	v_cmp_lt_u32_e64 s[4:5], v158, v238
	v_cmp_lt_u32_e64 s[6:7], v159, v239
	v_cmp_lt_u32_e64 s[8:9], v160, v240
	v_cmp_lt_u32_e64 s[28:29], v161, v241
	v_cndmask_b32_e64 v42, v42, v158, s[4:5]
	v_cndmask_b32_e64 v162, v162, 11, s[4:5]
	v_cndmask_b32_e64 v43, v43, v159, s[6:7]
	v_cndmask_b32_e64 v163, v163, 11, s[6:7]
	v_cndmask_b32_e64 v44, v44, v160, s[8:9]
	v_cndmask_b32_e64 v164, v164, 11, s[8:9]
	v_cndmask_b32_e64 v45, v45, v161, s[28:29]
	v_cndmask_b32_e64 v165, v165, 11, s[28:29]
	v_add_u32_sdwa v158, v173, v158 dst_sel:DWORD dst_unused:UNUSED_PAD src0_sel:WORD_1 src1_sel:DWORD
	v_add_u32_sdwa v159, v181, v159 dst_sel:DWORD dst_unused:UNUSED_PAD src0_sel:WORD_1 src1_sel:DWORD
	v_add_u32_sdwa v160, v189, v160 dst_sel:DWORD dst_unused:UNUSED_PAD src0_sel:WORD_1 src1_sel:DWORD
	v_add_u32_sdwa v161, v231, v161 dst_sel:DWORD dst_unused:UNUSED_PAD src0_sel:WORD_1 src1_sel:DWORD
	v_cmp_lt_u32_e64 s[4:5], v158, v238
	v_cmp_lt_u32_e64 s[6:7], v159, v239
	v_cmp_lt_u32_e64 s[8:9], v160, v240
	v_cmp_lt_u32_e64 s[28:29], v161, v241
	v_cndmask_b32_e64 v42, v42, v158, s[4:5]
	v_cndmask_b32_e64 v162, v162, 10, s[4:5]
	v_cndmask_b32_e64 v43, v43, v159, s[6:7]
	v_cndmask_b32_e64 v163, v163, 10, s[6:7]
	v_cndmask_b32_e64 v44, v44, v160, s[8:9]
	v_cndmask_b32_e64 v164, v164, 10, s[8:9]
	v_cndmask_b32_e64 v45, v45, v161, s[28:29]
	v_cndmask_b32_e64 v165, v165, 10, s[28:29]
	v_add_u32_sdwa v158, v173, v158 dst_sel:DWORD dst_unused:UNUSED_PAD src0_sel:WORD_0 src1_sel:DWORD
	v_add_u32_sdwa v159, v181, v159 dst_sel:DWORD dst_unused:UNUSED_PAD src0_sel:WORD_0 src1_sel:DWORD
	v_add_u32_sdwa v160, v189, v160 dst_sel:DWORD dst_unused:UNUSED_PAD src0_sel:WORD_0 src1_sel:DWORD
	v_add_u32_sdwa v161, v231, v161 dst_sel:DWORD dst_unused:UNUSED_PAD src0_sel:WORD_0 src1_sel:DWORD
	v_cmp_lt_u32_e64 s[4:5], v158, v238
	v_cmp_lt_u32_e64 s[6:7], v159, v239
	v_cmp_lt_u32_e64 s[8:9], v160, v240
	v_cmp_lt_u32_e64 s[28:29], v161, v241
	v_cndmask_b32_e64 v42, v42, v158, s[4:5]
	v_cndmask_b32_e64 v162, v162, 9, s[4:5]
	v_cndmask_b32_e64 v43, v43, v159, s[6:7]
	v_cndmask_b32_e64 v163, v163, 9, s[6:7]
	v_cndmask_b32_e64 v44, v44, v160, s[8:9]
	v_cndmask_b32_e64 v164, v164, 9, s[8:9]
	v_cndmask_b32_e64 v45, v45, v161, s[28:29]
	v_cndmask_b32_e64 v165, v165, 9, s[28:29]
	v_add_u32_sdwa v158, v172, v158 dst_sel:DWORD dst_unused:UNUSED_PAD src0_sel:WORD_1 src1_sel:DWORD
	v_add_u32_sdwa v159, v180, v159 dst_sel:DWORD dst_unused:UNUSED_PAD src0_sel:WORD_1 src1_sel:DWORD
	v_add_u32_sdwa v160, v188, v160 dst_sel:DWORD dst_unused:UNUSED_PAD src0_sel:WORD_1 src1_sel:DWORD
	v_add_u32_sdwa v161, v230, v161 dst_sel:DWORD dst_unused:UNUSED_PAD src0_sel:WORD_1 src1_sel:DWORD
	v_cmp_lt_u32_e64 s[4:5], v158, v238
	v_cmp_lt_u32_e64 s[6:7], v159, v239
	v_cmp_lt_u32_e64 s[8:9], v160, v240
	v_cmp_lt_u32_e64 s[28:29], v161, v241
	v_cndmask_b32_e64 v42, v42, v158, s[4:5]
	v_cndmask_b32_e64 v162, v162, 8, s[4:5]
	v_cndmask_b32_e64 v43, v43, v159, s[6:7]
	v_cndmask_b32_e64 v163, v163, 8, s[6:7]
	v_cndmask_b32_e64 v44, v44, v160, s[8:9]
	v_cndmask_b32_e64 v164, v164, 8, s[8:9]
	v_cndmask_b32_e64 v45, v45, v161, s[28:29]
; DI void idx_scan(const u32* hq, int need, u32* outbin, u32* outneed, int q, int lane) {
;     ...
;   if ((int)above < need && need <= (int)incl) {
;     u32 cum = above;
;     ...
;       u32 cnt = (hq[bin >> 1] >> ((bin & 1) * 16)) & 0xffffu;
;       if ((int)(cum + cnt) >= need) { outbin[q] = (u32)bin; outneed[q] = (u32)need - cum; break; }
;       cum += cnt;
;     }
	v_cndmask_b32_e64 v165, v165, 8, s[28:29]
	v_add_u32_sdwa v158, v172, v158 dst_sel:DWORD dst_unused:UNUSED_PAD src0_sel:WORD_0 src1_sel:DWORD
	v_add_u32_sdwa v159, v180, v159 dst_sel:DWORD dst_unused:UNUSED_PAD src0_sel:WORD_0 src1_sel:DWORD
	v_add_u32_sdwa v160, v188, v160 dst_sel:DWORD dst_unused:UNUSED_PAD src0_sel:WORD_0 src1_sel:DWORD
	v_add_u32_sdwa v161, v230, v161 dst_sel:DWORD dst_unused:UNUSED_PAD src0_sel:WORD_0 src1_sel:DWORD
	v_cmp_lt_u32_e64 s[4:5], v158, v238
	v_cmp_lt_u32_e64 s[6:7], v159, v239
	v_cmp_lt_u32_e64 s[8:9], v160, v240
	v_cmp_lt_u32_e64 s[28:29], v161, v241
	v_cndmask_b32_e64 v42, v42, v158, s[4:5]
	v_cndmask_b32_e64 v162, v162, 7, s[4:5]
	v_cndmask_b32_e64 v43, v43, v159, s[6:7]
	v_cndmask_b32_e64 v163, v163, 7, s[6:7]
	v_cndmask_b32_e64 v44, v44, v160, s[8:9]
	v_cndmask_b32_e64 v164, v164, 7, s[8:9]
	v_cndmask_b32_e64 v45, v45, v161, s[28:29]
	v_cndmask_b32_e64 v165, v165, 7, s[28:29]
	v_add_u32_sdwa v158, v171, v158 dst_sel:DWORD dst_unused:UNUSED_PAD src0_sel:WORD_1 src1_sel:DWORD
	v_add_u32_sdwa v159, v179, v159 dst_sel:DWORD dst_unused:UNUSED_PAD src0_sel:WORD_1 src1_sel:DWORD
	v_add_u32_sdwa v160, v187, v160 dst_sel:DWORD dst_unused:UNUSED_PAD src0_sel:WORD_1 src1_sel:DWORD
	v_add_u32_sdwa v161, v229, v161 dst_sel:DWORD dst_unused:UNUSED_PAD src0_sel:WORD_1 src1_sel:DWORD
	v_cmp_lt_u32_e64 s[4:5], v158, v238
	v_cmp_lt_u32_e64 s[6:7], v159, v239
	v_cmp_lt_u32_e64 s[8:9], v160, v240
	v_cmp_lt_u32_e64 s[28:29], v161, v241
	v_cndmask_b32_e64 v42, v42, v158, s[4:5]
	v_cndmask_b32_e64 v162, v162, 6, s[4:5]
	v_cndmask_b32_e64 v43, v43, v159, s[6:7]
	v_cndmask_b32_e64 v163, v163, 6, s[6:7]
	v_cndmask_b32_e64 v44, v44, v160, s[8:9]
	v_cndmask_b32_e64 v164, v164, 6, s[8:9]
	v_cndmask_b32_e64 v45, v45, v161, s[28:29]
	v_cndmask_b32_e64 v165, v165, 6, s[28:29]
	v_add_u32_sdwa v158, v171, v158 dst_sel:DWORD dst_unused:UNUSED_PAD src0_sel:WORD_0 src1_sel:DWORD
	v_add_u32_sdwa v159, v179, v159 dst_sel:DWORD dst_unused:UNUSED_PAD src0_sel:WORD_0 src1_sel:DWORD
	v_add_u32_sdwa v160, v187, v160 dst_sel:DWORD dst_unused:UNUSED_PAD src0_sel:WORD_0 src1_sel:DWORD
	v_add_u32_sdwa v161, v229, v161 dst_sel:DWORD dst_unused:UNUSED_PAD src0_sel:WORD_0 src1_sel:DWORD
	v_cmp_lt_u32_e64 s[4:5], v158, v238
	v_cmp_lt_u32_e64 s[6:7], v159, v239
	v_cmp_lt_u32_e64 s[8:9], v160, v240
	v_cmp_lt_u32_e64 s[28:29], v161, v241
	v_cndmask_b32_e64 v42, v42, v158, s[4:5]
	v_cndmask_b32_e64 v162, v162, 5, s[4:5]
	v_cndmask_b32_e64 v43, v43, v159, s[6:7]
	v_cndmask_b32_e64 v163, v163, 5, s[6:7]
	v_cndmask_b32_e64 v44, v44, v160, s[8:9]
	v_cndmask_b32_e64 v164, v164, 5, s[8:9]
	v_cndmask_b32_e64 v45, v45, v161, s[28:29]
	v_cndmask_b32_e64 v165, v165, 5, s[28:29]
	v_add_u32_sdwa v158, v170, v158 dst_sel:DWORD dst_unused:UNUSED_PAD src0_sel:WORD_1 src1_sel:DWORD
	v_add_u32_sdwa v159, v178, v159 dst_sel:DWORD dst_unused:UNUSED_PAD src0_sel:WORD_1 src1_sel:DWORD
	v_add_u32_sdwa v160, v186, v160 dst_sel:DWORD dst_unused:UNUSED_PAD src0_sel:WORD_1 src1_sel:DWORD
	v_add_u32_sdwa v161, v228, v161 dst_sel:DWORD dst_unused:UNUSED_PAD src0_sel:WORD_1 src1_sel:DWORD
	v_cmp_lt_u32_e64 s[4:5], v158, v238
	v_cmp_lt_u32_e64 s[6:7], v159, v239
	v_cmp_lt_u32_e64 s[8:9], v160, v240
	v_cmp_lt_u32_e64 s[28:29], v161, v241
	v_cndmask_b32_e64 v42, v42, v158, s[4:5]
	v_cndmask_b32_e64 v162, v162, 4, s[4:5]
	v_cndmask_b32_e64 v43, v43, v159, s[6:7]
	v_cndmask_b32_e64 v163, v163, 4, s[6:7]
	v_cndmask_b32_e64 v44, v44, v160, s[8:9]
	v_cndmask_b32_e64 v164, v164, 4, s[8:9]
	v_cndmask_b32_e64 v45, v45, v161, s[28:29]
	v_cndmask_b32_e64 v165, v165, 4, s[28:29]
	v_add_u32_sdwa v158, v170, v158 dst_sel:DWORD dst_unused:UNUSED_PAD src0_sel:WORD_0 src1_sel:DWORD
	v_add_u32_sdwa v159, v178, v159 dst_sel:DWORD dst_unused:UNUSED_PAD src0_sel:WORD_0 src1_sel:DWORD
	v_add_u32_sdwa v160, v186, v160 dst_sel:DWORD dst_unused:UNUSED_PAD src0_sel:WORD_0 src1_sel:DWORD
	v_add_u32_sdwa v161, v228, v161 dst_sel:DWORD dst_unused:UNUSED_PAD src0_sel:WORD_0 src1_sel:DWORD
	v_cmp_lt_u32_e64 s[4:5], v158, v238
	v_cmp_lt_u32_e64 s[6:7], v159, v239
	v_cmp_lt_u32_e64 s[8:9], v160, v240
	v_cmp_lt_u32_e64 s[28:29], v161, v241
	v_cndmask_b32_e64 v42, v42, v158, s[4:5]
	v_cndmask_b32_e64 v162, v162, 3, s[4:5]
	v_cndmask_b32_e64 v43, v43, v159, s[6:7]
	v_cndmask_b32_e64 v163, v163, 3, s[6:7]
	v_cndmask_b32_e64 v44, v44, v160, s[8:9]
	v_cndmask_b32_e64 v164, v164, 3, s[8:9]
; DI void idx_scan(const u32* hq, int need, u32* outbin, u32* outneed, int q, int lane) {
;     ...
;   if ((int)above < need && need <= (int)incl) {
;     u32 cum = above;
;     ...
;       u32 cnt = (hq[bin >> 1] >> ((bin & 1) * 16)) & 0xffffu;
;       if ((int)(cum + cnt) >= need) { outbin[q] = (u32)bin; outneed[q] = (u32)need - cum; break; }
;       cum += cnt;
;     }
; DI void idx_job(const Params& p, int b, int qg, unsigned char* smem) {
;     ...
;   for (int qq = 0; qq < 4; ++qq) idx_scan(hist + (wave * 4 + qq) * 512, 256, binA, needB, wave * 4 + qq, lane);
;   __syncthreads();
;   for (int i = tid; i < 8192; i += 256) hist[i] = 0u;
;   __syncthreads();
;   idx_pass<1>(kp, qf, wq, wave, ntile, lm, lg, tq, selall, binA[lm], 0u, hist, maskw, cand, ccnt);
	v_cndmask_b32_e64 v45, v45, v161, s[28:29]
	v_cndmask_b32_e64 v165, v165, 3, s[28:29]
	v_add_u32_sdwa v158, v169, v158 dst_sel:DWORD dst_unused:UNUSED_PAD src0_sel:WORD_1 src1_sel:DWORD
	v_add_u32_sdwa v159, v177, v159 dst_sel:DWORD dst_unused:UNUSED_PAD src0_sel:WORD_1 src1_sel:DWORD
	v_add_u32_sdwa v160, v185, v160 dst_sel:DWORD dst_unused:UNUSED_PAD src0_sel:WORD_1 src1_sel:DWORD
	v_add_u32_sdwa v161, v227, v161 dst_sel:DWORD dst_unused:UNUSED_PAD src0_sel:WORD_1 src1_sel:DWORD
	v_cmp_lt_u32_e64 s[4:5], v158, v238
	v_cmp_lt_u32_e64 s[6:7], v159, v239
	v_cmp_lt_u32_e64 s[8:9], v160, v240
	v_cmp_lt_u32_e64 s[28:29], v161, v241
	v_cndmask_b32_e64 v42, v42, v158, s[4:5]
	v_cndmask_b32_e64 v162, v162, 2, s[4:5]
	v_cndmask_b32_e64 v43, v43, v159, s[6:7]
	v_cndmask_b32_e64 v163, v163, 2, s[6:7]
	v_cndmask_b32_e64 v44, v44, v160, s[8:9]
	v_cndmask_b32_e64 v164, v164, 2, s[8:9]
	v_cndmask_b32_e64 v45, v45, v161, s[28:29]
	v_cndmask_b32_e64 v165, v165, 2, s[28:29]
	v_add_u32_sdwa v158, v169, v158 dst_sel:DWORD dst_unused:UNUSED_PAD src0_sel:WORD_0 src1_sel:DWORD
	v_add_u32_sdwa v159, v177, v159 dst_sel:DWORD dst_unused:UNUSED_PAD src0_sel:WORD_0 src1_sel:DWORD
	v_add_u32_sdwa v160, v185, v160 dst_sel:DWORD dst_unused:UNUSED_PAD src0_sel:WORD_0 src1_sel:DWORD
	v_add_u32_sdwa v161, v227, v161 dst_sel:DWORD dst_unused:UNUSED_PAD src0_sel:WORD_0 src1_sel:DWORD
	v_cmp_lt_u32_e64 s[4:5], v158, v238
	v_cmp_lt_u32_e64 s[6:7], v159, v239
	v_cmp_lt_u32_e64 s[8:9], v160, v240
	v_cmp_lt_u32_e64 s[28:29], v161, v241
	v_cndmask_b32_e64 v42, v42, v158, s[4:5]
	v_cndmask_b32_e64 v162, v162, 1, s[4:5]
	v_cndmask_b32_e64 v43, v43, v159, s[6:7]
	v_cndmask_b32_e64 v163, v163, 1, s[6:7]
	v_cndmask_b32_e64 v44, v44, v160, s[8:9]
	v_cndmask_b32_e64 v164, v164, 1, s[8:9]
	v_cndmask_b32_e64 v45, v45, v161, s[28:29]
	v_cndmask_b32_e64 v165, v165, 1, s[28:29]
	v_add_u32_sdwa v158, v168, v158 dst_sel:DWORD dst_unused:UNUSED_PAD src0_sel:WORD_1 src1_sel:DWORD
	v_add_u32_sdwa v159, v176, v159 dst_sel:DWORD dst_unused:UNUSED_PAD src0_sel:WORD_1 src1_sel:DWORD
	v_add_u32_sdwa v160, v184, v160 dst_sel:DWORD dst_unused:UNUSED_PAD src0_sel:WORD_1 src1_sel:DWORD
	v_add_u32_sdwa v161, v226, v161 dst_sel:DWORD dst_unused:UNUSED_PAD src0_sel:WORD_1 src1_sel:DWORD
	v_cmp_lt_u32_e64 s[4:5], v158, v238
	v_cmp_lt_u32_e64 s[6:7], v159, v239
	v_cmp_lt_u32_e64 s[8:9], v160, v240
	v_cmp_lt_u32_e64 s[28:29], v161, v241
	v_cndmask_b32_e64 v42, v42, v158, s[4:5]
	v_cndmask_b32_e64 v162, v162, 0, s[4:5]
	v_cndmask_b32_e64 v43, v43, v159, s[6:7]
	v_cndmask_b32_e64 v163, v163, 0, s[6:7]
	v_cndmask_b32_e64 v44, v44, v160, s[8:9]
	v_cndmask_b32_e64 v164, v164, 0, s[8:9]
	v_cndmask_b32_e64 v45, v45, v161, s[28:29]
	v_cndmask_b32_e64 v165, v165, 0, s[28:29]
	v_add_u32_sdwa v158, v168, v158 dst_sel:DWORD dst_unused:UNUSED_PAD src0_sel:WORD_0 src1_sel:DWORD
	v_add_u32_sdwa v159, v176, v159 dst_sel:DWORD dst_unused:UNUSED_PAD src0_sel:WORD_0 src1_sel:DWORD
	v_add_u32_sdwa v160, v184, v160 dst_sel:DWORD dst_unused:UNUSED_PAD src0_sel:WORD_0 src1_sel:DWORD
	v_add_u32_sdwa v161, v226, v161 dst_sel:DWORD dst_unused:UNUSED_PAD src0_sel:WORD_0 src1_sel:DWORD
	v_cmp_lt_u32_e64 s[4:5], v158, v238
	v_cmp_lt_u32_e64 s[6:7], v159, v239
	v_cmp_lt_u32_e64 s[8:9], v160, v240
	v_cmp_lt_u32_e64 s[28:29], v161, v241
	v_cndmask_b32_e64 v42, v42, v158, s[4:5]
	v_cndmask_b32_e64 v162, v162, -1, s[4:5]
	v_cndmask_b32_e64 v43, v43, v159, s[6:7]
	v_cndmask_b32_e64 v163, v163, -1, s[6:7]
	v_cndmask_b32_e64 v44, v44, v160, s[8:9]
	v_cndmask_b32_e64 v164, v164, -1, s[8:9]
	v_cndmask_b32_e64 v45, v45, v161, s[28:29]
	v_cndmask_b32_e64 v165, v165, -1, s[28:29]
	v_lshl_add_u32 v50, v48, 4, v162
	v_lshl_add_u32 v51, v48, 4, v163
	v_lshl_add_u32 v52, v48, 4, v164
	v_lshl_add_u32 v53, v48, 4, v165
	v_sub_u32_e32 v54, v238, v42
	v_sub_u32_e32 v55, v239, v43
	v_sub_u32_e32 v242, v240, v44
	v_sub_u32_e32 v243, v241, v45
	s_mov_b64 exec, s[40:41]
	ds_write2_b32 v47, v50, v54 offset0:80 offset1:96
	s_mov_b64 exec, s[42:43]
	ds_write2_b32 v47, v51, v55 offset0:81 offset1:97
	s_mov_b64 exec, s[44:45]
	ds_write2_b32 v47, v52, v242 offset0:82 offset1:98
	s_mov_b64 exec, s[46:47]
	ds_write2_b32 v47, v53, v243 offset0:83 offset1:99
	s_mov_b64 exec, -1
	s_waitcnt lgkmcnt(0)
	s_barrier
	s_cbranch_vccnz .Lidx1_pj
	global_load_dwordx4 v[42:45], v[92:93], off
	global_load_dwordx4 v[46:49], v[94:95], off
